# GEMM K loops: one-dword touch load 256 B ahead of every LDS-DMA tile load (L2 warm-up one iteration ahead), counted waits re-derived (17 / 18,16)
# baseline (speedup 1.0000x reference)
.LBB0_331:
	s_lshl_b32 s1, s7, 5
	s_and_b32 s1, s1, 0x60
	s_lshl_b32 s86, s2, 6
	s_lshl_b32 s0, s2, 13
	s_lshl_b32 s7, s1, 7
	s_add_u32 s82, s16, 0x20100000
	s_addc_u32 s83, s17, 0
	s_add_i32 m0, s67, 0x18000
	v_lshl_add_u64 v[2:3], v[2:3], 0, s[94:95]
	s_waitcnt vmcnt(2)
	s_barrier
	global_load_lds_dwordx4 v[2:3], off
	v_lshl_add_u64 v[2:3], v[4:5], 0, s[94:95]
	s_add_i32 m0, s67, 0x1a000
	s_add_i32 s87, s67, 0x8000
	global_load_lds_dwordx4 v[2:3], off
	v_lshl_add_u64 v[2:3], v[10:11], 0, s[94:95]
	s_mov_b32 m0, s87
	s_add_i32 s2, s67, 0xa000
	global_load_lds_dwordx4 v[2:3], off
	v_lshl_add_u64 v[2:3], v[12:13], 0, s[94:95]
	s_mov_b32 m0, s2
	v_and_b32_e32 v188, 15, v222
	global_load_lds_dwordx4 v[2:3], off
	s_add_i32 m0, s67, 0x1c000
	v_lshl_add_u64 v[2:3], v[6:7], 0, s[94:95]
	global_load_lds_dwordx4 v[2:3], off
	v_lshl_add_u64 v[2:3], v[8:9], 0, s[94:95]
	s_add_i32 m0, s67, 0x1e000
	v_lshlrev_b32_e32 v4, 2, v222
	global_load_lds_dwordx4 v[2:3], off
	v_bfe_u32 v2, v222, 4, 2
	v_lshlrev_b32_e32 v3, 4, v2
	s_cmpk_lt_u32 s9, 0x100
	v_lshl_or_b32 v3, v188, 6, v3
	v_and_b32_e32 v4, 32, v4
	s_cselect_b64 s[84:85], -1, 0
	s_lshl_b32 s35, s35, 3
	v_bitop3_b32 v5, v3, s0, v4 bitop3:0xde
	v_bitop3_b32 v223, s7, v3, v4 bitop3:0xf6
	v_cvt_f32_u32_e32 v3, s35
	v_cmp_gt_u32_e64 s[14:15], 2, v188
	s_lshr_b32 s73, s3, 6
	s_lshr_b32 s3, s3, 10
	v_writelane_b32 v245, s14, 62
	s_and_b32 s34, s34, 4
	s_lshr_b32 s0, s8, 3
	v_writelane_b32 v245, s15, 63
	s_add_u32 s14, s92, 0x5800
	v_rcp_iflag_f32_e32 v3, v3
	s_addc_u32 s15, s93, 0
	v_writelane_b32 v244, s14, 30
	v_add_u32_e32 v0, v18, v0
	v_mul_f32_e32 v3, 0x4f7ffffe, v3
	v_writelane_b32 v244, s15, 31
	s_add_u32 s14, s92, 0xb000
	s_addc_u32 s15, s93, 0
	v_writelane_b32 v244, s14, 32
	v_cvt_u32_f32_e32 v3, v3
	v_writelane_b32 v245, s0, 60
	v_writelane_b32 v244, s15, 33
	s_add_u32 s14, s16, 0x20d60000
	s_addc_u32 s15, s17, 0
	s_add_u32 s74, s16, 0x219c0000
	s_addc_u32 s75, s17, 0
	v_lshl_or_b32 v224, v2, 3, s1
	v_lshl_or_b32 v225, v2, 2, s1
	s_sub_i32 s0, 0, s35
	v_readfirstlane_b32 s1, v3
	v_add_lshl_u32 v0, v0, v17, 1
	s_waitcnt vmcnt(6)
	s_mul_i32 s0, s0, s1
	v_lshl_add_u64 v[192:193], s[90:91], 0, v[0:1]
	v_add_u32_e32 v0, v16, v14
	v_writelane_b32 v244, s14, 34
	s_mul_hi_u32 s0, s1, s0
	v_add_lshl_u32 v0, v0, v15, 1
	v_cmp_lt_u32_e64 s[42:43], 1, v188
	v_cmp_lt_u32_e64 s[44:45], 13, v188
	v_add_u32_e32 v190, -14, v188
	s_mov_b32 s7, s89
	s_mov_b32 s9, s89
	v_writelane_b32 v244, s15, 35
	s_mov_b32 s80, 0
	s_add_i32 s0, s1, s0
	v_lshl_add_u64 v[194:195], s[90:91], 0, v[0:1]
	v_add_u32_e32 v226, 0, v5
	s_barrier
	v_writelane_b32 v244, s0, 36
	global_load_dword v239, v1, s[48:49]
	s_branch .LBB0_334
.Lrk_344:
	s_add_i32 vcc_lo, s50, 2
	s_add_u32 s68, s48, 0x80
	s_addc_u32 s51, s49, 0
	s_add_i32 s70, 0, 0x10000
	s_cmp_eq_u32 s15, s50
	s_cselect_b32 s51, s1, s51
	s_cselect_b32 s50, s0, s68
	v_add_u32_e32 v0, s70, v223
	s_cselect_b32 s69, s53, s57
	s_cselect_b32 s68, s52, s56
	s_add_i32 s71, 0, 0x14000
	ds_read_b128 v[130:133], v0
	ds_read_b128 v[134:137], v0 offset:1024
	ds_read_b128 v[138:141], v0 offset:2048
	ds_read_b128 v[142:145], v0 offset:3072
	v_add_u32_e32 v0, s71, v223
	ds_read_b128 v[146:149], v0
	ds_read_b128 v[150:153], v0 offset:1024
	ds_read_b128 v[154:157], v0 offset:2048
	ds_read_b128 v[158:161], v0 offset:3072
	s_add_i32 s98, vcc_lo, -2
	s_lshr_b32 s99, s98, 3
	s_lshl_b32 s99, s99, 17
	s_and_b32 vcc_hi, s98, 2
	s_lshl_b32 vcc_hi, vcc_hi, 5
	s_or_b32 s99, s99, vcc_hi
	s_and_b32 vcc_hi, s98, 4
	s_lshl_b32 vcc_hi, vcc_hi, 7
	s_or_b32 s98, s99, vcc_hi
	s_add_u32 s98, s100, s98
	s_addc_u32 s99, s101, 0
	s_nop 0
	global_load_dwordx4 v[240:243], v238, s[98:99]
	v_lshl_add_u64 v[212:213], s[48:49], 0, v[192:193]
	s_add_i32 m0, s67, 0xc000
	ds_read_b128 v[162:165], v226
	ds_read_b128 v[166:169], v226 offset:1024
	ds_read_b128 v[170:173], v226 offset:2048
	ds_read_b128 v[174:177], v226 offset:3072
	ds_read_b128 v[196:199], v226 offset:4096
	ds_read_b128 v[200:203], v226 offset:5120
	ds_read_b128 v[204:207], v226 offset:6144
	ds_read_b128 v[208:211], v226 offset:7168
	global_load_lds_dwordx4 v[212:213], off
	global_load_dword v239, v[212:213], off offset:256
	v_lshl_add_u64 v[212:213], s[48:49], 0, v[194:195]
	s_add_i32 m0, s67, 0xe000
	s_nop 0
	global_load_lds_dwordx4 v[212:213], off
	global_load_dword v239, v[212:213], off offset:256
	s_waitcnt vmcnt(18)
	s_waitcnt lgkmcnt(0)
	s_barrier
	s_setprio 1
	s_waitcnt lgkmcnt(0)
	v_mfma_f32_16x16x32_bf16 v[126:129], v[130:133], v[162:165], v[126:129]
	v_mfma_f32_16x16x32_bf16 v[122:125], v[138:141], v[162:165], v[122:125]
	v_mfma_f32_16x16x32_bf16 v[118:121], v[130:133], v[170:173], v[118:121]
	v_mfma_f32_16x16x32_bf16 v[114:117], v[138:141], v[170:173], v[114:117]
	v_mfma_f32_16x16x32_bf16 v[102:105], v[130:133], v[196:199], v[102:105]
	v_mfma_f32_16x16x32_bf16 v[98:101], v[138:141], v[196:199], v[98:101]
	v_mfma_f32_16x16x32_bf16 v[86:89], v[130:133], v[204:207], v[86:89]
	v_mfma_f32_16x16x32_bf16 v[82:85], v[138:141], v[204:207], v[82:85]
	v_mfma_f32_16x16x32_bf16 v[126:129], v[134:137], v[166:169], v[126:129]
	v_mfma_f32_16x16x32_bf16 v[122:125], v[142:145], v[166:169], v[122:125]
	v_mfma_f32_16x16x32_bf16 v[118:121], v[134:137], v[174:177], v[118:121]
	v_mfma_f32_16x16x32_bf16 v[114:117], v[142:145], v[174:177], v[114:117]
	v_mfma_f32_16x16x32_bf16 v[102:105], v[134:137], v[200:203], v[102:105]
	v_mfma_f32_16x16x32_bf16 v[98:101], v[142:145], v[200:203], v[98:101]
	v_mfma_f32_16x16x32_bf16 v[86:89], v[134:137], v[208:211], v[86:89]
	v_mfma_f32_16x16x32_bf16 v[82:85], v[142:145], v[208:211], v[82:85]
	s_setprio 0
	s_setprio 1
	v_mfma_f32_16x16x32_bf16 v[110:113], v[146:149], v[162:165], v[110:113]
	v_mfma_f32_16x16x32_bf16 v[106:109], v[154:157], v[162:165], v[106:109]
	v_mfma_f32_16x16x32_bf16 v[94:97], v[146:149], v[170:173], v[94:97]
	v_mfma_f32_16x16x32_bf16 v[90:93], v[154:157], v[170:173], v[90:93]
	v_mfma_f32_16x16x32_bf16 v[78:81], v[146:149], v[196:199], v[78:81]
	v_mfma_f32_16x16x32_bf16 v[74:77], v[154:157], v[196:199], v[74:77]
	v_mfma_f32_16x16x32_bf16 v[70:73], v[146:149], v[204:207], v[70:73]
	v_mfma_f32_16x16x32_bf16 v[66:69], v[154:157], v[204:207], v[66:69]
	v_mfma_f32_16x16x32_bf16 v[110:113], v[150:153], v[166:169], v[110:113]
	v_mfma_f32_16x16x32_bf16 v[106:109], v[158:161], v[166:169], v[106:109]
	v_mfma_f32_16x16x32_bf16 v[94:97], v[150:153], v[174:177], v[94:97]
	v_mfma_f32_16x16x32_bf16 v[90:93], v[158:161], v[174:177], v[90:93]
	v_mfma_f32_16x16x32_bf16 v[78:81], v[150:153], v[200:203], v[78:81]
	v_mfma_f32_16x16x32_bf16 v[74:77], v[158:161], v[200:203], v[74:77]
	v_mfma_f32_16x16x32_bf16 v[70:73], v[150:153], v[208:211], v[70:73]
	v_mfma_f32_16x16x32_bf16 v[66:69], v[158:161], v[208:211], v[66:69]
	s_setprio 0
	s_barrier
	s_add_i32 s70, s70, s63
	v_lshl_add_u64 v[212:213], s[68:69], 0, v[186:187]
	s_mov_b32 m0, s70
	ds_read_b128 v[162:165], v226 offset:16384
	ds_read_b128 v[166:169], v226 offset:17408
	ds_read_b128 v[170:173], v226 offset:18432
	ds_read_b128 v[174:177], v226 offset:19456
	ds_read_b128 v[196:199], v226 offset:20480
	ds_read_b128 v[200:203], v226 offset:21504
	ds_read_b128 v[204:207], v226 offset:22528
	ds_read_b128 v[208:211], v226 offset:23552
	global_load_lds_dwordx4 v[212:213], off
	global_load_dword v239, v[212:213], off offset:256
	s_add_i32 m0, s70, 0x2000
	v_lshl_add_u64 v[214:215], s[68:69], 0, v[182:183]
	s_add_u32 s68, s68, s90
	s_addc_u32 s69, s69, 0
	s_add_i32 s70, s71, s63
	global_load_lds_dwordx4 v[214:215], off
	global_load_dword v239, v[214:215], off offset:256
	v_lshl_add_u64 v[216:217], s[68:69], 0, v[186:187]
	s_mov_b32 m0, s70
	v_lshl_add_u64 v[218:219], s[68:69], 0, v[182:183]
	global_load_lds_dwordx4 v[216:217], off
	global_load_dword v239, v[216:217], off offset:256
	s_add_i32 m0, s70, 0x2000
	v_lshl_add_u64 v[232:233], s[50:51], 0, v[184:185]
	global_load_lds_dwordx4 v[218:219], off
	global_load_dword v239, v[218:219], off offset:256
	s_mov_b32 m0, s67
	v_lshl_add_u64 v[234:235], s[50:51], 0, v[180:181]
	global_load_lds_dwordx4 v[232:233], off
	global_load_dword v239, v[232:233], off offset:256
	s_mov_b32 m0, s33
	s_nop 0
	global_load_lds_dwordx4 v[234:235], off
	global_load_dword v239, v[234:235], off offset:256
	s_waitcnt vmcnt(16)
	s_add_i32 s98, vcc_lo, -2
	s_cmp_lt_u32 s98, 16
	s_cbranch_scc0 .Lrk_dU_8_16
	s_cmp_lt_u32 s98, 8
	s_cbranch_scc0 .Lrk_dU_4_8
	s_cmp_lt_u32 s98, 4
	s_cbranch_scc0 .Lrk_dU_2_4
	s_cmp_lt_u32 s98, 2
	s_cbranch_scc0 .Lrk_dU_1_2
	v_pk_add_f32 v[126:127], v[126:127], v[240:241]
	v_pk_add_f32 v[128:129], v[128:129], v[242:243]
	s_branch .Lrk_joinU

.Lrk_joinU:
	s_waitcnt lgkmcnt(0)
	s_barrier
	s_setprio 1
	s_waitcnt lgkmcnt(0)
	v_mfma_f32_16x16x32_bf16 v[62:65], v[130:133], v[162:165], v[62:65]
	v_mfma_f32_16x16x32_bf16 v[58:61], v[138:141], v[162:165], v[58:61]
	v_mfma_f32_16x16x32_bf16 v[54:57], v[130:133], v[170:173], v[54:57]
	v_mfma_f32_16x16x32_bf16 v[50:53], v[138:141], v[170:173], v[50:53]
	v_mfma_f32_16x16x32_bf16 v[38:41], v[130:133], v[196:199], v[38:41]
	v_mfma_f32_16x16x32_bf16 v[34:37], v[138:141], v[196:199], v[34:37]
	v_mfma_f32_16x16x32_bf16 v[22:25], v[130:133], v[204:207], v[22:25]
	v_mfma_f32_16x16x32_bf16 v[18:21], v[138:141], v[204:207], v[18:21]
	v_mfma_f32_16x16x32_bf16 v[62:65], v[134:137], v[166:169], v[62:65]
	v_mfma_f32_16x16x32_bf16 v[58:61], v[142:145], v[166:169], v[58:61]
	v_mfma_f32_16x16x32_bf16 v[54:57], v[134:137], v[174:177], v[54:57]
	v_mfma_f32_16x16x32_bf16 v[50:53], v[142:145], v[174:177], v[50:53]
	v_mfma_f32_16x16x32_bf16 v[38:41], v[134:137], v[200:203], v[38:41]
	v_mfma_f32_16x16x32_bf16 v[34:37], v[142:145], v[200:203], v[34:37]
	v_mfma_f32_16x16x32_bf16 v[22:25], v[134:137], v[208:211], v[22:25]
	v_mfma_f32_16x16x32_bf16 v[18:21], v[142:145], v[208:211], v[18:21]
	s_setprio 0
	s_setprio 1
	v_mfma_f32_16x16x32_bf16 v[46:49], v[146:149], v[162:165], v[46:49]
	v_mfma_f32_16x16x32_bf16 v[42:45], v[154:157], v[162:165], v[42:45]
	v_mfma_f32_16x16x32_bf16 v[30:33], v[146:149], v[170:173], v[30:33]
	v_mfma_f32_16x16x32_bf16 v[26:29], v[154:157], v[170:173], v[26:29]
	v_mfma_f32_16x16x32_bf16 v[14:17], v[146:149], v[196:199], v[14:17]
	v_mfma_f32_16x16x32_bf16 v[10:13], v[154:157], v[196:199], v[10:13]
	v_mfma_f32_16x16x32_bf16 v[6:9], v[146:149], v[204:207], v[6:9]
	v_mfma_f32_16x16x32_bf16 v[2:5], v[154:157], v[204:207], v[2:5]
	v_mfma_f32_16x16x32_bf16 v[46:49], v[150:153], v[166:169], v[46:49]
	v_mfma_f32_16x16x32_bf16 v[42:45], v[158:161], v[166:169], v[42:45]
	v_mfma_f32_16x16x32_bf16 v[30:33], v[150:153], v[174:177], v[30:33]
	v_mfma_f32_16x16x32_bf16 v[26:29], v[158:161], v[174:177], v[26:29]
	v_mfma_f32_16x16x32_bf16 v[14:17], v[150:153], v[200:203], v[14:17]
	v_mfma_f32_16x16x32_bf16 v[10:13], v[158:161], v[200:203], v[10:13]
	v_mfma_f32_16x16x32_bf16 v[6:9], v[150:153], v[208:211], v[6:9]
	v_mfma_f32_16x16x32_bf16 v[2:5], v[158:161], v[208:211], v[2:5]
	s_setprio 0
	s_barrier
	s_add_i32 s68, 0, 0x18000
	v_add_u32_e32 v0, s68, v223
	s_add_i32 s69, 0, 0x1c000
	ds_read_b128 v[130:133], v0
	ds_read_b128 v[134:137], v0 offset:1024
	ds_read_b128 v[138:141], v0 offset:2048
	ds_read_b128 v[142:145], v0 offset:3072
	v_add_u32_e32 v0, s69, v223
	ds_read_b128 v[146:149], v0
	ds_read_b128 v[150:153], v0 offset:1024
	ds_read_b128 v[154:157], v0 offset:2048
	ds_read_b128 v[158:161], v0 offset:3072
	s_add_u32 s50, s50, s90
	s_addc_u32 s51, s51, 0
	s_mov_b32 m0, s65
	s_add_i32 s98, vcc_lo, -2
	s_lshr_b32 s99, s98, 3
	s_lshl_b32 s99, s99, 17
	s_and_b32 vcc_hi, s98, 2
	s_lshl_b32 vcc_hi, vcc_hi, 5
	s_or_b32 s99, s99, vcc_hi
	s_and_b32 vcc_hi, s98, 4
	s_lshl_b32 vcc_hi, vcc_hi, 7
	s_or_b32 s98, s99, vcc_hi
	s_add_u32 s98, s98, 0x100000
	s_add_u32 s98, s100, s98
	s_addc_u32 s99, s101, 0
	s_nop 0
	global_load_dwordx4 v[240:243], v238, s[98:99]
	v_lshl_add_u64 v[236:237], s[50:51], 0, v[184:185]
	ds_read_b128 v[162:165], v226 offset:32768
	ds_read_b128 v[166:169], v226 offset:33792
	ds_read_b128 v[170:173], v226 offset:34816
	ds_read_b128 v[174:177], v226 offset:35840
	ds_read_b128 v[196:199], v226 offset:36864
	ds_read_b128 v[200:203], v226 offset:37888
	ds_read_b128 v[204:207], v226 offset:38912
	ds_read_b128 v[208:211], v226 offset:39936
	global_load_lds_dwordx4 v[236:237], off
	global_load_dword v239, v[236:237], off offset:256
	v_lshl_add_u64 v[236:237], s[50:51], 0, v[180:181]
	s_mov_b32 m0, s22
	s_nop 0
	global_load_lds_dwordx4 v[236:237], off
	global_load_dword v239, v[236:237], off offset:256
	s_waitcnt vmcnt(18)
	s_waitcnt lgkmcnt(0)
	s_barrier
	s_setprio 1
	s_waitcnt lgkmcnt(0)
	v_mfma_f32_16x16x32_bf16 v[126:129], v[130:133], v[162:165], v[126:129]
	v_mfma_f32_16x16x32_bf16 v[122:125], v[138:141], v[162:165], v[122:125]
	v_mfma_f32_16x16x32_bf16 v[118:121], v[130:133], v[170:173], v[118:121]
	v_mfma_f32_16x16x32_bf16 v[114:117], v[138:141], v[170:173], v[114:117]
	v_mfma_f32_16x16x32_bf16 v[102:105], v[130:133], v[196:199], v[102:105]
	v_mfma_f32_16x16x32_bf16 v[98:101], v[138:141], v[196:199], v[98:101]
	v_mfma_f32_16x16x32_bf16 v[86:89], v[130:133], v[204:207], v[86:89]
	v_mfma_f32_16x16x32_bf16 v[82:85], v[138:141], v[204:207], v[82:85]
	v_mfma_f32_16x16x32_bf16 v[126:129], v[134:137], v[166:169], v[126:129]
	v_mfma_f32_16x16x32_bf16 v[122:125], v[142:145], v[166:169], v[122:125]
	v_mfma_f32_16x16x32_bf16 v[118:121], v[134:137], v[174:177], v[118:121]
	v_mfma_f32_16x16x32_bf16 v[114:117], v[142:145], v[174:177], v[114:117]
	v_mfma_f32_16x16x32_bf16 v[102:105], v[134:137], v[200:203], v[102:105]
	v_mfma_f32_16x16x32_bf16 v[98:101], v[142:145], v[200:203], v[98:101]
	v_mfma_f32_16x16x32_bf16 v[86:89], v[134:137], v[208:211], v[86:89]
	v_mfma_f32_16x16x32_bf16 v[82:85], v[142:145], v[208:211], v[82:85]
	s_setprio 0
	s_setprio 1
	v_mfma_f32_16x16x32_bf16 v[110:113], v[146:149], v[162:165], v[110:113]
	v_mfma_f32_16x16x32_bf16 v[106:109], v[154:157], v[162:165], v[106:109]
	v_mfma_f32_16x16x32_bf16 v[94:97], v[146:149], v[170:173], v[94:97]
	v_mfma_f32_16x16x32_bf16 v[90:93], v[154:157], v[170:173], v[90:93]
	v_mfma_f32_16x16x32_bf16 v[78:81], v[146:149], v[196:199], v[78:81]
	v_mfma_f32_16x16x32_bf16 v[74:77], v[154:157], v[196:199], v[74:77]
	v_mfma_f32_16x16x32_bf16 v[70:73], v[146:149], v[204:207], v[70:73]
	v_mfma_f32_16x16x32_bf16 v[66:69], v[154:157], v[204:207], v[66:69]
	v_mfma_f32_16x16x32_bf16 v[110:113], v[150:153], v[166:169], v[110:113]
	v_mfma_f32_16x16x32_bf16 v[106:109], v[158:161], v[166:169], v[106:109]
	v_mfma_f32_16x16x32_bf16 v[94:97], v[150:153], v[174:177], v[94:97]
	v_mfma_f32_16x16x32_bf16 v[90:93], v[158:161], v[174:177], v[90:93]
	v_mfma_f32_16x16x32_bf16 v[78:81], v[150:153], v[200:203], v[78:81]
	v_mfma_f32_16x16x32_bf16 v[74:77], v[158:161], v[200:203], v[74:77]
	v_mfma_f32_16x16x32_bf16 v[70:73], v[150:153], v[208:211], v[70:73]
	v_mfma_f32_16x16x32_bf16 v[66:69], v[158:161], v[208:211], v[66:69]
	s_setprio 0
	s_barrier
	s_add_i32 s50, s68, s63
	v_lshl_add_u64 v[212:213], v[212:213], 0, s[94:95]
	s_mov_b32 m0, s50
	ds_read_b128 v[162:165], v226 offset:49152
	ds_read_b128 v[166:169], v226 offset:50176
	ds_read_b128 v[170:173], v226 offset:51200
	ds_read_b128 v[174:177], v226 offset:52224
	ds_read_b128 v[196:199], v226 offset:53248
	ds_read_b128 v[200:203], v226 offset:54272
	ds_read_b128 v[204:207], v226 offset:55296
	ds_read_b128 v[208:211], v226 offset:56320
	global_load_lds_dwordx4 v[212:213], off
	global_load_dword v239, v[212:213], off offset:256
	v_lshl_add_u64 v[212:213], v[214:215], 0, s[94:95]
	s_add_i32 m0, s50, 0x2000
	s_add_i32 s50, s69, s63
	global_load_lds_dwordx4 v[212:213], off
	global_load_dword v239, v[212:213], off offset:256
	v_lshl_add_u64 v[212:213], v[216:217], 0, s[94:95]
	s_mov_b32 m0, s50
	s_nop 0
	global_load_lds_dwordx4 v[212:213], off
	global_load_dword v239, v[212:213], off offset:256
	v_lshl_add_u64 v[212:213], v[218:219], 0, s[94:95]
	s_add_i32 m0, s50, 0x2000
	s_nop 0
	global_load_lds_dwordx4 v[212:213], off
	global_load_dword v239, v[212:213], off offset:256
	v_lshl_add_u64 v[212:213], v[232:233], 0, s[94:95]
	s_mov_b32 m0, s87
	s_nop 0
	global_load_lds_dwordx4 v[212:213], off
	global_load_dword v239, v[212:213], off offset:256
	v_lshl_add_u64 v[212:213], v[234:235], 0, s[94:95]
	s_mov_b32 m0, s2
	s_nop 0
	global_load_lds_dwordx4 v[212:213], off
	global_load_dword v239, v[212:213], off offset:256
	s_waitcnt vmcnt(16)
	s_add_i32 s98, vcc_lo, -2
	s_cmp_lt_u32 s98, 16
	s_cbranch_scc0 .Lrk_dL_8_16
	s_cmp_lt_u32 s98, 8
	s_cbranch_scc0 .Lrk_dL_4_8
	s_cmp_lt_u32 s98, 4
	s_cbranch_scc0 .Lrk_dL_2_4
	s_cmp_lt_u32 s98, 2
	s_cbranch_scc0 .Lrk_dL_1_2
	v_pk_add_f32 v[62:63], v[62:63], v[240:241]
	v_pk_add_f32 v[64:65], v[64:65], v[242:243]
	s_branch .Lrk_joinL

.LBB0_344:
	s_add_i32 vcc_lo, s50, 2
	s_add_u32 s68, s48, 0x80
	s_addc_u32 s51, s49, 0
	s_add_i32 s70, 0, 0x10000
	s_cmp_eq_u32 s15, s50
	s_cselect_b32 s51, s1, s51
	s_cselect_b32 s50, s0, s68
	v_add_u32_e32 v0, s70, v223
	s_cselect_b32 s69, s53, s57
	s_cselect_b32 s68, s52, s56
	s_add_i32 s71, 0, 0x14000
	ds_read_b128 v[130:133], v0
	ds_read_b128 v[134:137], v0 offset:1024
	ds_read_b128 v[138:141], v0 offset:2048
	ds_read_b128 v[142:145], v0 offset:3072
	v_add_u32_e32 v0, s71, v223
	ds_read_b128 v[146:149], v0
	ds_read_b128 v[150:153], v0 offset:1024
	ds_read_b128 v[154:157], v0 offset:2048
	ds_read_b128 v[158:161], v0 offset:3072
	v_lshl_add_u64 v[212:213], s[48:49], 0, v[192:193]
	s_add_i32 m0, s67, 0xc000
	ds_read_b128 v[162:165], v226
	ds_read_b128 v[166:169], v226 offset:1024
	ds_read_b128 v[170:173], v226 offset:2048
	ds_read_b128 v[174:177], v226 offset:3072
	ds_read_b128 v[196:199], v226 offset:4096
	ds_read_b128 v[200:203], v226 offset:5120
	ds_read_b128 v[204:207], v226 offset:6144
	ds_read_b128 v[208:211], v226 offset:7168
	global_load_lds_dwordx4 v[212:213], off
	global_load_dword v239, v[212:213], off offset:256
	v_lshl_add_u64 v[212:213], s[48:49], 0, v[194:195]
	s_add_i32 m0, s67, 0xe000
	s_nop 0
	global_load_lds_dwordx4 v[212:213], off
	global_load_dword v239, v[212:213], off offset:256
	s_waitcnt vmcnt(17)
	s_waitcnt lgkmcnt(0)
	s_barrier
	s_setprio 1
	s_waitcnt lgkmcnt(0)
	v_mfma_f32_16x16x32_bf16 v[126:129], v[130:133], v[162:165], v[126:129]
	v_mfma_f32_16x16x32_bf16 v[122:125], v[138:141], v[162:165], v[122:125]
	v_mfma_f32_16x16x32_bf16 v[118:121], v[130:133], v[170:173], v[118:121]
	v_mfma_f32_16x16x32_bf16 v[114:117], v[138:141], v[170:173], v[114:117]
	v_mfma_f32_16x16x32_bf16 v[102:105], v[130:133], v[196:199], v[102:105]
	v_mfma_f32_16x16x32_bf16 v[98:101], v[138:141], v[196:199], v[98:101]
	v_mfma_f32_16x16x32_bf16 v[86:89], v[130:133], v[204:207], v[86:89]
	v_mfma_f32_16x16x32_bf16 v[82:85], v[138:141], v[204:207], v[82:85]
	v_mfma_f32_16x16x32_bf16 v[126:129], v[134:137], v[166:169], v[126:129]
	v_mfma_f32_16x16x32_bf16 v[122:125], v[142:145], v[166:169], v[122:125]
	v_mfma_f32_16x16x32_bf16 v[118:121], v[134:137], v[174:177], v[118:121]
	v_mfma_f32_16x16x32_bf16 v[114:117], v[142:145], v[174:177], v[114:117]
	v_mfma_f32_16x16x32_bf16 v[102:105], v[134:137], v[200:203], v[102:105]
	v_mfma_f32_16x16x32_bf16 v[98:101], v[142:145], v[200:203], v[98:101]
	v_mfma_f32_16x16x32_bf16 v[86:89], v[134:137], v[208:211], v[86:89]
	v_mfma_f32_16x16x32_bf16 v[82:85], v[142:145], v[208:211], v[82:85]
	s_setprio 0
	s_setprio 1
	v_mfma_f32_16x16x32_bf16 v[110:113], v[146:149], v[162:165], v[110:113]
	v_mfma_f32_16x16x32_bf16 v[106:109], v[154:157], v[162:165], v[106:109]
	v_mfma_f32_16x16x32_bf16 v[94:97], v[146:149], v[170:173], v[94:97]
	v_mfma_f32_16x16x32_bf16 v[90:93], v[154:157], v[170:173], v[90:93]
	v_mfma_f32_16x16x32_bf16 v[78:81], v[146:149], v[196:199], v[78:81]
	v_mfma_f32_16x16x32_bf16 v[74:77], v[154:157], v[196:199], v[74:77]
	v_mfma_f32_16x16x32_bf16 v[70:73], v[146:149], v[204:207], v[70:73]
	v_mfma_f32_16x16x32_bf16 v[66:69], v[154:157], v[204:207], v[66:69]
	v_mfma_f32_16x16x32_bf16 v[110:113], v[150:153], v[166:169], v[110:113]
	v_mfma_f32_16x16x32_bf16 v[106:109], v[158:161], v[166:169], v[106:109]
	v_mfma_f32_16x16x32_bf16 v[94:97], v[150:153], v[174:177], v[94:97]
	v_mfma_f32_16x16x32_bf16 v[90:93], v[158:161], v[174:177], v[90:93]
	v_mfma_f32_16x16x32_bf16 v[78:81], v[150:153], v[200:203], v[78:81]
	v_mfma_f32_16x16x32_bf16 v[74:77], v[158:161], v[200:203], v[74:77]
	v_mfma_f32_16x16x32_bf16 v[70:73], v[150:153], v[208:211], v[70:73]
	v_mfma_f32_16x16x32_bf16 v[66:69], v[158:161], v[208:211], v[66:69]
	s_setprio 0
	s_barrier
	s_add_i32 s70, s70, s63
	v_lshl_add_u64 v[212:213], s[68:69], 0, v[186:187]
	s_mov_b32 m0, s70
	ds_read_b128 v[162:165], v226 offset:16384
	ds_read_b128 v[166:169], v226 offset:17408
	ds_read_b128 v[170:173], v226 offset:18432
	ds_read_b128 v[174:177], v226 offset:19456
	ds_read_b128 v[196:199], v226 offset:20480
	ds_read_b128 v[200:203], v226 offset:21504
	ds_read_b128 v[204:207], v226 offset:22528
	ds_read_b128 v[208:211], v226 offset:23552
	global_load_lds_dwordx4 v[212:213], off
	global_load_dword v239, v[212:213], off offset:256
	s_add_i32 m0, s70, 0x2000
	v_lshl_add_u64 v[214:215], s[68:69], 0, v[182:183]
	s_add_u32 s68, s68, s90
	s_addc_u32 s69, s69, 0
	s_add_i32 s70, s71, s63
	global_load_lds_dwordx4 v[214:215], off
	global_load_dword v239, v[214:215], off offset:256
	v_lshl_add_u64 v[216:217], s[68:69], 0, v[186:187]
	s_mov_b32 m0, s70
	v_lshl_add_u64 v[218:219], s[68:69], 0, v[182:183]
	global_load_lds_dwordx4 v[216:217], off
	global_load_dword v239, v[216:217], off offset:256
	s_add_i32 m0, s70, 0x2000
	v_lshl_add_u64 v[232:233], s[50:51], 0, v[184:185]
	global_load_lds_dwordx4 v[218:219], off
	global_load_dword v239, v[218:219], off offset:256
	s_mov_b32 m0, s67
	v_lshl_add_u64 v[234:235], s[50:51], 0, v[180:181]
	global_load_lds_dwordx4 v[232:233], off
	global_load_dword v239, v[232:233], off offset:256
	s_mov_b32 m0, s33
	s_nop 0
	global_load_lds_dwordx4 v[234:235], off
	global_load_dword v239, v[234:235], off offset:256
	s_waitcnt vmcnt(17)
	s_waitcnt lgkmcnt(0)
	s_barrier
	s_setprio 1
	s_waitcnt lgkmcnt(0)
	v_mfma_f32_16x16x32_bf16 v[62:65], v[130:133], v[162:165], v[62:65]
	v_mfma_f32_16x16x32_bf16 v[58:61], v[138:141], v[162:165], v[58:61]
	v_mfma_f32_16x16x32_bf16 v[54:57], v[130:133], v[170:173], v[54:57]
	v_mfma_f32_16x16x32_bf16 v[50:53], v[138:141], v[170:173], v[50:53]
	v_mfma_f32_16x16x32_bf16 v[38:41], v[130:133], v[196:199], v[38:41]
	v_mfma_f32_16x16x32_bf16 v[34:37], v[138:141], v[196:199], v[34:37]
	v_mfma_f32_16x16x32_bf16 v[22:25], v[130:133], v[204:207], v[22:25]
	v_mfma_f32_16x16x32_bf16 v[18:21], v[138:141], v[204:207], v[18:21]
	v_mfma_f32_16x16x32_bf16 v[62:65], v[134:137], v[166:169], v[62:65]
	v_mfma_f32_16x16x32_bf16 v[58:61], v[142:145], v[166:169], v[58:61]
	v_mfma_f32_16x16x32_bf16 v[54:57], v[134:137], v[174:177], v[54:57]
	v_mfma_f32_16x16x32_bf16 v[50:53], v[142:145], v[174:177], v[50:53]
	v_mfma_f32_16x16x32_bf16 v[38:41], v[134:137], v[200:203], v[38:41]
	v_mfma_f32_16x16x32_bf16 v[34:37], v[142:145], v[200:203], v[34:37]
	v_mfma_f32_16x16x32_bf16 v[22:25], v[134:137], v[208:211], v[22:25]
	v_mfma_f32_16x16x32_bf16 v[18:21], v[142:145], v[208:211], v[18:21]
	s_setprio 0
	s_setprio 1
	v_mfma_f32_16x16x32_bf16 v[46:49], v[146:149], v[162:165], v[46:49]
	v_mfma_f32_16x16x32_bf16 v[42:45], v[154:157], v[162:165], v[42:45]
	v_mfma_f32_16x16x32_bf16 v[30:33], v[146:149], v[170:173], v[30:33]
	v_mfma_f32_16x16x32_bf16 v[26:29], v[154:157], v[170:173], v[26:29]
	v_mfma_f32_16x16x32_bf16 v[14:17], v[146:149], v[196:199], v[14:17]
	v_mfma_f32_16x16x32_bf16 v[10:13], v[154:157], v[196:199], v[10:13]
	v_mfma_f32_16x16x32_bf16 v[6:9], v[146:149], v[204:207], v[6:9]
	v_mfma_f32_16x16x32_bf16 v[2:5], v[154:157], v[204:207], v[2:5]
	v_mfma_f32_16x16x32_bf16 v[46:49], v[150:153], v[166:169], v[46:49]
	v_mfma_f32_16x16x32_bf16 v[42:45], v[158:161], v[166:169], v[42:45]
	v_mfma_f32_16x16x32_bf16 v[30:33], v[150:153], v[174:177], v[30:33]
	v_mfma_f32_16x16x32_bf16 v[26:29], v[158:161], v[174:177], v[26:29]
	v_mfma_f32_16x16x32_bf16 v[14:17], v[150:153], v[200:203], v[14:17]
	v_mfma_f32_16x16x32_bf16 v[10:13], v[158:161], v[200:203], v[10:13]
	v_mfma_f32_16x16x32_bf16 v[6:9], v[150:153], v[208:211], v[6:9]
	v_mfma_f32_16x16x32_bf16 v[2:5], v[158:161], v[208:211], v[2:5]
	s_setprio 0
	s_barrier
	s_add_i32 s68, 0, 0x18000
	v_add_u32_e32 v0, s68, v223
	s_add_i32 s69, 0, 0x1c000
	ds_read_b128 v[130:133], v0
	ds_read_b128 v[134:137], v0 offset:1024
	ds_read_b128 v[138:141], v0 offset:2048
	ds_read_b128 v[142:145], v0 offset:3072
	v_add_u32_e32 v0, s69, v223
	ds_read_b128 v[146:149], v0
	ds_read_b128 v[150:153], v0 offset:1024
	ds_read_b128 v[154:157], v0 offset:2048
	ds_read_b128 v[158:161], v0 offset:3072
	s_add_u32 s50, s50, s90
	s_addc_u32 s51, s51, 0
	s_mov_b32 m0, s65
	v_lshl_add_u64 v[236:237], s[50:51], 0, v[184:185]
	ds_read_b128 v[162:165], v226 offset:32768
	ds_read_b128 v[166:169], v226 offset:33792
	ds_read_b128 v[170:173], v226 offset:34816
	ds_read_b128 v[174:177], v226 offset:35840
	ds_read_b128 v[196:199], v226 offset:36864
	ds_read_b128 v[200:203], v226 offset:37888
	ds_read_b128 v[204:207], v226 offset:38912
	ds_read_b128 v[208:211], v226 offset:39936
	global_load_lds_dwordx4 v[236:237], off
	global_load_dword v239, v[236:237], off offset:256
	v_lshl_add_u64 v[236:237], s[50:51], 0, v[180:181]
	s_mov_b32 m0, s22
	s_nop 0
	global_load_lds_dwordx4 v[236:237], off
	global_load_dword v239, v[236:237], off offset:256
	s_waitcnt vmcnt(17)
	s_waitcnt lgkmcnt(0)
	s_barrier
	s_setprio 1
	s_waitcnt lgkmcnt(0)
	v_mfma_f32_16x16x32_bf16 v[126:129], v[130:133], v[162:165], v[126:129]
	v_mfma_f32_16x16x32_bf16 v[122:125], v[138:141], v[162:165], v[122:125]
	v_mfma_f32_16x16x32_bf16 v[118:121], v[130:133], v[170:173], v[118:121]
	v_mfma_f32_16x16x32_bf16 v[114:117], v[138:141], v[170:173], v[114:117]
	v_mfma_f32_16x16x32_bf16 v[102:105], v[130:133], v[196:199], v[102:105]
	v_mfma_f32_16x16x32_bf16 v[98:101], v[138:141], v[196:199], v[98:101]
	v_mfma_f32_16x16x32_bf16 v[86:89], v[130:133], v[204:207], v[86:89]
	v_mfma_f32_16x16x32_bf16 v[82:85], v[138:141], v[204:207], v[82:85]
	v_mfma_f32_16x16x32_bf16 v[126:129], v[134:137], v[166:169], v[126:129]
	v_mfma_f32_16x16x32_bf16 v[122:125], v[142:145], v[166:169], v[122:125]
	v_mfma_f32_16x16x32_bf16 v[118:121], v[134:137], v[174:177], v[118:121]
	v_mfma_f32_16x16x32_bf16 v[114:117], v[142:145], v[174:177], v[114:117]
	v_mfma_f32_16x16x32_bf16 v[102:105], v[134:137], v[200:203], v[102:105]
	v_mfma_f32_16x16x32_bf16 v[98:101], v[142:145], v[200:203], v[98:101]
	v_mfma_f32_16x16x32_bf16 v[86:89], v[134:137], v[208:211], v[86:89]
	v_mfma_f32_16x16x32_bf16 v[82:85], v[142:145], v[208:211], v[82:85]
	s_setprio 0
	s_setprio 1
	v_mfma_f32_16x16x32_bf16 v[110:113], v[146:149], v[162:165], v[110:113]
	v_mfma_f32_16x16x32_bf16 v[106:109], v[154:157], v[162:165], v[106:109]
	v_mfma_f32_16x16x32_bf16 v[94:97], v[146:149], v[170:173], v[94:97]
	v_mfma_f32_16x16x32_bf16 v[90:93], v[154:157], v[170:173], v[90:93]
	v_mfma_f32_16x16x32_bf16 v[78:81], v[146:149], v[196:199], v[78:81]
	v_mfma_f32_16x16x32_bf16 v[74:77], v[154:157], v[196:199], v[74:77]
	v_mfma_f32_16x16x32_bf16 v[70:73], v[146:149], v[204:207], v[70:73]
	v_mfma_f32_16x16x32_bf16 v[66:69], v[154:157], v[204:207], v[66:69]
	v_mfma_f32_16x16x32_bf16 v[110:113], v[150:153], v[166:169], v[110:113]
	v_mfma_f32_16x16x32_bf16 v[106:109], v[158:161], v[166:169], v[106:109]
	v_mfma_f32_16x16x32_bf16 v[94:97], v[150:153], v[174:177], v[94:97]
	v_mfma_f32_16x16x32_bf16 v[90:93], v[158:161], v[174:177], v[90:93]
	v_mfma_f32_16x16x32_bf16 v[78:81], v[150:153], v[200:203], v[78:81]
	v_mfma_f32_16x16x32_bf16 v[74:77], v[158:161], v[200:203], v[74:77]
	v_mfma_f32_16x16x32_bf16 v[70:73], v[150:153], v[208:211], v[70:73]
	v_mfma_f32_16x16x32_bf16 v[66:69], v[158:161], v[208:211], v[66:69]
	s_setprio 0
	s_barrier
	s_add_i32 s50, s68, s63
	v_lshl_add_u64 v[212:213], v[212:213], 0, s[94:95]
	s_mov_b32 m0, s50
	ds_read_b128 v[162:165], v226 offset:49152
	ds_read_b128 v[166:169], v226 offset:50176
	ds_read_b128 v[170:173], v226 offset:51200
	ds_read_b128 v[174:177], v226 offset:52224
	ds_read_b128 v[196:199], v226 offset:53248
	ds_read_b128 v[200:203], v226 offset:54272
	ds_read_b128 v[204:207], v226 offset:55296
	ds_read_b128 v[208:211], v226 offset:56320
	global_load_lds_dwordx4 v[212:213], off
	global_load_dword v239, v[212:213], off offset:256
	v_lshl_add_u64 v[212:213], v[214:215], 0, s[94:95]
	s_add_i32 m0, s50, 0x2000
	s_add_i32 s50, s69, s63
	global_load_lds_dwordx4 v[212:213], off
	global_load_dword v239, v[212:213], off offset:256
	v_lshl_add_u64 v[212:213], v[216:217], 0, s[94:95]
	s_mov_b32 m0, s50
	s_nop 0
	global_load_lds_dwordx4 v[212:213], off
	global_load_dword v239, v[212:213], off offset:256
	v_lshl_add_u64 v[212:213], v[218:219], 0, s[94:95]
	s_add_i32 m0, s50, 0x2000
	s_nop 0
	global_load_lds_dwordx4 v[212:213], off
	global_load_dword v239, v[212:213], off offset:256
	v_lshl_add_u64 v[212:213], v[232:233], 0, s[94:95]
	s_mov_b32 m0, s87
	s_nop 0
	global_load_lds_dwordx4 v[212:213], off
	global_load_dword v239, v[212:213], off offset:256
	v_lshl_add_u64 v[212:213], v[234:235], 0, s[94:95]
	s_mov_b32 m0, s2
	s_nop 0
	global_load_lds_dwordx4 v[212:213], off
	global_load_dword v239, v[212:213], off offset:256
	s_waitcnt vmcnt(17)
	s_waitcnt lgkmcnt(0)
	s_barrier
	s_setprio 1
	s_waitcnt lgkmcnt(0)
	v_mfma_f32_16x16x32_bf16 v[62:65], v[130:133], v[162:165], v[62:65]
	v_mfma_f32_16x16x32_bf16 v[58:61], v[138:141], v[162:165], v[58:61]
	v_mfma_f32_16x16x32_bf16 v[54:57], v[130:133], v[170:173], v[54:57]
	v_mfma_f32_16x16x32_bf16 v[50:53], v[138:141], v[170:173], v[50:53]
	v_mfma_f32_16x16x32_bf16 v[38:41], v[130:133], v[196:199], v[38:41]
	v_mfma_f32_16x16x32_bf16 v[34:37], v[138:141], v[196:199], v[34:37]
	v_mfma_f32_16x16x32_bf16 v[22:25], v[130:133], v[204:207], v[22:25]
	v_mfma_f32_16x16x32_bf16 v[18:21], v[138:141], v[204:207], v[18:21]
	v_mfma_f32_16x16x32_bf16 v[62:65], v[134:137], v[166:169], v[62:65]
	v_mfma_f32_16x16x32_bf16 v[58:61], v[142:145], v[166:169], v[58:61]
	v_mfma_f32_16x16x32_bf16 v[54:57], v[134:137], v[174:177], v[54:57]
	v_mfma_f32_16x16x32_bf16 v[50:53], v[142:145], v[174:177], v[50:53]
	v_mfma_f32_16x16x32_bf16 v[38:41], v[134:137], v[200:203], v[38:41]
	v_mfma_f32_16x16x32_bf16 v[34:37], v[142:145], v[200:203], v[34:37]
	v_mfma_f32_16x16x32_bf16 v[22:25], v[134:137], v[208:211], v[22:25]
	v_mfma_f32_16x16x32_bf16 v[18:21], v[142:145], v[208:211], v[18:21]
	s_setprio 0
	s_setprio 1
	v_mfma_f32_16x16x32_bf16 v[46:49], v[146:149], v[162:165], v[46:49]
	v_mfma_f32_16x16x32_bf16 v[42:45], v[154:157], v[162:165], v[42:45]
	v_mfma_f32_16x16x32_bf16 v[30:33], v[146:149], v[170:173], v[30:33]
	v_mfma_f32_16x16x32_bf16 v[26:29], v[154:157], v[170:173], v[26:29]
	v_mfma_f32_16x16x32_bf16 v[14:17], v[146:149], v[196:199], v[14:17]
	v_mfma_f32_16x16x32_bf16 v[10:13], v[154:157], v[196:199], v[10:13]
	v_mfma_f32_16x16x32_bf16 v[6:9], v[146:149], v[204:207], v[6:9]
	v_mfma_f32_16x16x32_bf16 v[2:5], v[154:157], v[204:207], v[2:5]
	v_mfma_f32_16x16x32_bf16 v[46:49], v[150:153], v[166:169], v[46:49]
	v_mfma_f32_16x16x32_bf16 v[42:45], v[158:161], v[166:169], v[42:45]
	v_mfma_f32_16x16x32_bf16 v[30:33], v[150:153], v[174:177], v[30:33]
	v_mfma_f32_16x16x32_bf16 v[26:29], v[158:161], v[174:177], v[26:29]
	v_mfma_f32_16x16x32_bf16 v[14:17], v[150:153], v[200:203], v[14:17]
	v_mfma_f32_16x16x32_bf16 v[10:13], v[158:161], v[200:203], v[10:13]
	v_mfma_f32_16x16x32_bf16 v[6:9], v[150:153], v[208:211], v[6:9]
	v_mfma_f32_16x16x32_bf16 v[2:5], v[158:161], v[208:211], v[2:5]
	s_setprio 0
	s_barrier
	s_add_u32 s48, s48, 0x100
	s_addc_u32 s49, s49, 0
	s_add_u32 s56, s56, 0x100
	s_addc_u32 s57, s57, 0
	s_cmp_ge_i32 vcc_lo, s55
	s_mov_b32 s50, vcc_lo
	s_cbranch_scc0 .LBB0_344
